# FF1 deferred epilogue stores with state-dependent exact vmcnt waits (9/10/11) so the K-loop prefetch depth is unchanged
# baseline (speedup 1.0000x reference)
; #define PG8_STAGE(bufoff, gbase, voff) do { _Pragma("unroll") for (int _i = 0; _i < 2; ++_i) \
;         __builtin_amdgcn_global_load_lds((const unsigned*)((const char*)(gbase) + (voff)[_i]), (PG8_LAS unsigned*)(lds + (bufoff) + ldsw + _i * 8192), 16, 0, 0); } while (0)
; #define PG8_LDA(dst, b, h) do { _Pragma("unroll") for (int m = 0; m < 4; ++m) _Pragma("unroll") for (int k = 0; k < 2; ++k) dst[m][k] = *(const PG8_LAS bf16x8*)(lds + PG8_SA(b, h) + aoff + m * 2048 + k * 1024); } while (0)
; #define PG8_LDB(dst, b, h) do { _Pragma("unroll") for (int n = 0; n < 2; ++n) _Pragma("unroll") for (int k = 0; k < 2; ++k) dst[n][k] = *(const PG8_LAS bf16x8*)(lds + PG8_SB(b, h) + boff + n * 2048 + k * 1024); } while (0)
; #define PG8_MMA(ai, bj, At, Bt) do { __builtin_amdgcn_s_setprio(1); _Pragma("unroll") for (int m = 0; m < 4; ++m) _Pragma("unroll") for (int n = 0; n < 2; ++n) _Pragma("unroll") for (int k = 0; k < 2; ++k) \
;         acc[ai][bj][m][n] = __builtin_amdgcn_mfma_f32_16x16x32_bf16(Bt[n][k], At[m][k], acc[ai][bj][m][n], 0, 0, 0); __builtin_amdgcn_s_setprio(0); } while (0)
; #define PG8_WAIT_V(n) asm volatile("s_waitcnt vmcnt(" #n ")" ::: "memory")
; #define PG8_WAIT_L(n) asm volatile("s_waitcnt lgkmcnt(" #n ")" ::: "memory")
; #define PG8_BAR __builtin_amdgcn_s_barrier()
; #define PG8_SCHED __builtin_amdgcn_sched_barrier(0)
; template <class Epi, class Sched, bool ALIGN_EPI = false, bool SP2 = false>
; __device__ __forceinline__ void gemm_phase(PG8_LAS unsigned char* lds, const Gemm g, const Sched& S, const Epi& E) {
;     ...
;             PG8_LDB(B0, 0, 0); PG8_LDB(B1, 0, 1); PG8_SCHED; PG8_LDA(At, 0, 0); PG8_STAGE(PG8_SA(1, 1), a1 + hstep, voffA);
;             PG8_WAIT_V(8); PG8_WAIT_L(0); PG8_BAR; PG8_MMA(0, 0, At, B0); PG8_MMA(0, 1, At, B1); PG8_BAR; PG8_SCHED;
;             PG8_LDA(At, 0, 1); PG8_STAGE(PG8_SB(0, 0), b2, voffB); PG8_STAGE(PG8_SB(0, 1), b2 + hstep, voffB); PG8_STAGE(PG8_SA(0, 0), a2, voffA);
.LBB0_714:
	ds_read_b128 v[154:157], v147
	ds_read_b128 v[158:161], v147 offset:1024
	ds_read_b128 v[162:165], v147 offset:2048
	ds_read_b128 v[166:169], v147 offset:3072
	ds_read_b128 v[170:173], v148
	ds_read_b128 v[174:177], v148 offset:1024
	ds_read_b128 v[178:181], v148 offset:2048
	ds_read_b128 v[182:185], v148 offset:3072
	s_add_u32 s33, s40, 0xfffc0080
	s_addc_u32 s34, s41, -1
	s_cmp_eq_u32 s76, 12
	s_cselect_b32 s45, s23, s34
	s_cselect_b32 s44, s72, s33
	s_cselect_b32 s43, s21, s75
	s_cselect_b32 s42, s73, s74
	v_lshl_add_u64 v[150:151], s[40:41], 0, v[136:137]
	s_add_i32 m0, s39, 0xc000
	ds_read_b128 v[186:189], v149
	ds_read_b128 v[190:193], v149 offset:1024
	ds_read_b128 v[194:197], v149 offset:2048
	ds_read_b128 v[198:201], v149 offset:3072
	ds_read_b128 v[202:205], v149 offset:4096
	ds_read_b128 v[206:209], v149 offset:5120
	ds_read_b128 v[210:213], v149 offset:6144
	ds_read_b128 v[214:217], v149 offset:7168
	global_load_lds_dwordx4 v[150:151], off
	v_lshl_add_u64 v[150:151], s[40:41], 0, v[138:139]
	s_add_i32 m0, s39, 0xe000
	s_nop 0
	global_load_lds_dwordx4 v[150:151], off
	s_cmp_eq_u32 s77, 0
	s_cbranch_scc1 .Lds7_0_a
	s_cmp_eq_u32 s77, 4
	s_cbranch_scc1 .Lds7_0_b
	s_waitcnt vmcnt(8)
.Lds7_0_ret:
	s_waitcnt lgkmcnt(0)
	s_barrier
	s_setprio 1
	s_waitcnt lgkmcnt(0)
	v_mfma_f32_16x16x32_bf16 v[124:127], v[154:157], v[186:189], v[124:127]
	v_mfma_f32_16x16x32_bf16 v[116:119], v[162:165], v[186:189], v[116:119]
	v_mfma_f32_16x16x32_bf16 v[108:111], v[154:157], v[194:197], v[108:111]
	v_mfma_f32_16x16x32_bf16 v[100:103], v[162:165], v[194:197], v[100:103]
	v_mfma_f32_16x16x32_bf16 v[92:95], v[154:157], v[202:205], v[92:95]
	v_mfma_f32_16x16x32_bf16 v[84:87], v[162:165], v[202:205], v[84:87]
	v_mfma_f32_16x16x32_bf16 v[76:79], v[154:157], v[210:213], v[76:79]
	v_mfma_f32_16x16x32_bf16 v[68:71], v[162:165], v[210:213], v[68:71]
	v_mfma_f32_16x16x32_bf16 v[124:127], v[158:161], v[190:193], v[124:127]
	v_mfma_f32_16x16x32_bf16 v[116:119], v[166:169], v[190:193], v[116:119]
	v_mfma_f32_16x16x32_bf16 v[108:111], v[158:161], v[198:201], v[108:111]
	v_mfma_f32_16x16x32_bf16 v[100:103], v[166:169], v[198:201], v[100:103]
	v_mfma_f32_16x16x32_bf16 v[92:95], v[158:161], v[206:209], v[92:95]
	v_mfma_f32_16x16x32_bf16 v[84:87], v[166:169], v[206:209], v[84:87]
	v_mfma_f32_16x16x32_bf16 v[76:79], v[158:161], v[214:217], v[76:79]
	v_mfma_f32_16x16x32_bf16 v[68:71], v[166:169], v[214:217], v[68:71]
	s_setprio 0
	s_setprio 1
	v_mfma_f32_16x16x32_bf16 v[120:123], v[170:173], v[186:189], v[120:123]
	v_mfma_f32_16x16x32_bf16 v[112:115], v[178:181], v[186:189], v[112:115]
	v_mfma_f32_16x16x32_bf16 v[104:107], v[170:173], v[194:197], v[104:107]
	v_mfma_f32_16x16x32_bf16 v[96:99], v[178:181], v[194:197], v[96:99]
	v_mfma_f32_16x16x32_bf16 v[88:91], v[170:173], v[202:205], v[88:91]
	v_mfma_f32_16x16x32_bf16 v[80:83], v[178:181], v[202:205], v[80:83]
	v_mfma_f32_16x16x32_bf16 v[72:75], v[170:173], v[210:213], v[72:75]
	v_mfma_f32_16x16x32_bf16 v[64:67], v[178:181], v[210:213], v[64:67]
	v_mfma_f32_16x16x32_bf16 v[120:123], v[174:177], v[190:193], v[120:123]
	v_mfma_f32_16x16x32_bf16 v[112:115], v[182:185], v[190:193], v[112:115]
	v_mfma_f32_16x16x32_bf16 v[104:107], v[174:177], v[198:201], v[104:107]
	v_mfma_f32_16x16x32_bf16 v[96:99], v[182:185], v[198:201], v[96:99]
	v_mfma_f32_16x16x32_bf16 v[88:91], v[174:177], v[206:209], v[88:91]
	v_mfma_f32_16x16x32_bf16 v[80:83], v[182:185], v[206:209], v[80:83]
	v_mfma_f32_16x16x32_bf16 v[72:75], v[174:177], v[214:217], v[72:75]
	v_mfma_f32_16x16x32_bf16 v[64:67], v[182:185], v[214:217], v[64:67]
	s_setprio 0
	s_barrier
	s_add_i32 s33, s62, s52
	v_lshl_add_u64 v[150:151], s[42:43], 0, v[130:131]
	s_mov_b32 m0, s33
	ds_read_b128 v[186:189], v149 offset:16384
	ds_read_b128 v[190:193], v149 offset:17408
	ds_read_b128 v[194:197], v149 offset:18432
	ds_read_b128 v[198:201], v149 offset:19456
	ds_read_b128 v[202:205], v149 offset:20480
	ds_read_b128 v[206:209], v149 offset:21504
	ds_read_b128 v[210:213], v149 offset:22528
	ds_read_b128 v[214:217], v149 offset:23552
	global_load_lds_dwordx4 v[150:151], off
	s_add_i32 m0, s33, 0x2000
	s_add_u32 s78, s42, 0x40000
	v_lshl_add_u64 v[218:219], s[42:43], 0, v[134:135]
	s_addc_u32 s79, s43, 0
	s_add_i32 s33, s63, s52
	global_load_lds_dwordx4 v[218:219], off
	v_lshl_add_u64 v[220:221], s[78:79], 0, v[130:131]
	s_mov_b32 m0, s33
	v_lshl_add_u64 v[222:223], s[44:45], 0, v[132:133]
	global_load_lds_dwordx4 v[220:221], off
	v_lshl_add_u64 v[220:221], s[78:79], 0, v[134:135]
	s_add_i32 m0, s33, 0x2000
	s_nop 0
	global_load_lds_dwordx4 v[220:221], off
	v_lshl_add_u64 v[220:221], s[44:45], 0, v[128:129]
	s_mov_b32 m0, s39
	s_nop 0
	global_load_lds_dwordx4 v[220:221], off
	s_mov_b32 m0, s55
	s_nop 0
	global_load_lds_dwordx4 v[222:223], off
	s_cmp_eq_u32 s77, 1
	s_cbranch_scc1 .Lds7_1_a
	s_cmp_eq_u32 s77, 5
	s_cbranch_scc1 .Lds7_1_b
	s_waitcnt vmcnt(8)
; #define PG8_STAGE(bufoff, gbase, voff) do { _Pragma("unroll") for (int _i = 0; _i < 2; ++_i) \
;         __builtin_amdgcn_global_load_lds((const unsigned*)((const char*)(gbase) + (voff)[_i]), (PG8_LAS unsigned*)(lds + (bufoff) + ldsw + _i * 8192), 16, 0, 0); } while (0)
; #define PG8_LDA(dst, b, h) do { _Pragma("unroll") for (int m = 0; m < 4; ++m) _Pragma("unroll") for (int k = 0; k < 2; ++k) dst[m][k] = *(const PG8_LAS bf16x8*)(lds + PG8_SA(b, h) + aoff + m * 2048 + k * 1024); } while (0)
; #define PG8_LDB(dst, b, h) do { _Pragma("unroll") for (int n = 0; n < 2; ++n) _Pragma("unroll") for (int k = 0; k < 2; ++k) dst[n][k] = *(const PG8_LAS bf16x8*)(lds + PG8_SB(b, h) + boff + n * 2048 + k * 1024); } while (0)
; #define PG8_MMA(ai, bj, At, Bt) do { __builtin_amdgcn_s_setprio(1); _Pragma("unroll") for (int m = 0; m < 4; ++m) _Pragma("unroll") for (int n = 0; n < 2; ++n) _Pragma("unroll") for (int k = 0; k < 2; ++k) \
;         acc[ai][bj][m][n] = __builtin_amdgcn_mfma_f32_16x16x32_bf16(Bt[n][k], At[m][k], acc[ai][bj][m][n], 0, 0, 0); __builtin_amdgcn_s_setprio(0); } while (0)
; #define PG8_WAIT_V(n) asm volatile("s_waitcnt vmcnt(" #n ")" ::: "memory")
; #define PG8_WAIT_L(n) asm volatile("s_waitcnt lgkmcnt(" #n ")" ::: "memory")
; #define PG8_BAR __builtin_amdgcn_s_barrier()
; #define PG8_SCHED __builtin_amdgcn_sched_barrier(0)
; template <class Epi, class Sched, bool ALIGN_EPI = false, bool SP2 = false>
; __device__ __forceinline__ void gemm_phase(PG8_LAS unsigned char* lds, const Gemm g, const Sched& S, const Epi& E) {
;     ...
;             PG8_LDA(At, 0, 1); PG8_STAGE(PG8_SB(0, 0), b2, voffB); PG8_STAGE(PG8_SB(0, 1), b2 + hstep, voffB); PG8_STAGE(PG8_SA(0, 0), a2, voffA);
;             PG8_WAIT_V(8); PG8_WAIT_L(0); PG8_BAR; PG8_MMA(1, 0, At, B0); PG8_MMA(1, 1, At, B1); PG8_BAR; PG8_SCHED;
;             PG8_LDB(B0, 1, 0); PG8_LDB(B1, 1, 1); PG8_SCHED; PG8_LDA(At, 1, 0); PG8_STAGE(PG8_SA(0, 1), a2 + hstep, voffA);
.Lds7_1_ret:
	s_waitcnt lgkmcnt(0)
	s_barrier
	s_setprio 1
	s_waitcnt lgkmcnt(0)
	v_mfma_f32_16x16x32_bf16 v[60:63], v[154:157], v[186:189], v[60:63]
	v_mfma_f32_16x16x32_bf16 v[52:55], v[162:165], v[186:189], v[52:55]
	v_mfma_f32_16x16x32_bf16 v[44:47], v[154:157], v[194:197], v[44:47]
	v_mfma_f32_16x16x32_bf16 v[36:39], v[162:165], v[194:197], v[36:39]
	v_mfma_f32_16x16x32_bf16 v[28:31], v[154:157], v[202:205], v[28:31]
	v_mfma_f32_16x16x32_bf16 v[20:23], v[162:165], v[202:205], v[20:23]
	v_mfma_f32_16x16x32_bf16 v[12:15], v[154:157], v[210:213], v[12:15]
	v_mfma_f32_16x16x32_bf16 v[4:7], v[162:165], v[210:213], v[4:7]
	v_mfma_f32_16x16x32_bf16 v[60:63], v[158:161], v[190:193], v[60:63]
	v_mfma_f32_16x16x32_bf16 v[52:55], v[166:169], v[190:193], v[52:55]
	v_mfma_f32_16x16x32_bf16 v[44:47], v[158:161], v[198:201], v[44:47]
	v_mfma_f32_16x16x32_bf16 v[36:39], v[166:169], v[198:201], v[36:39]
	v_mfma_f32_16x16x32_bf16 v[28:31], v[158:161], v[206:209], v[28:31]
	v_mfma_f32_16x16x32_bf16 v[20:23], v[166:169], v[206:209], v[20:23]
	v_mfma_f32_16x16x32_bf16 v[12:15], v[158:161], v[214:217], v[12:15]
	v_mfma_f32_16x16x32_bf16 v[4:7], v[166:169], v[214:217], v[4:7]
	s_setprio 0
	s_setprio 1
	v_mfma_f32_16x16x32_bf16 v[56:59], v[170:173], v[186:189], v[56:59]
	v_mfma_f32_16x16x32_bf16 v[48:51], v[178:181], v[186:189], v[48:51]
	v_mfma_f32_16x16x32_bf16 v[40:43], v[170:173], v[194:197], v[40:43]
	v_mfma_f32_16x16x32_bf16 v[32:35], v[178:181], v[194:197], v[32:35]
	v_mfma_f32_16x16x32_bf16 v[24:27], v[170:173], v[202:205], v[24:27]
	v_mfma_f32_16x16x32_bf16 v[16:19], v[178:181], v[202:205], v[16:19]
	v_mfma_f32_16x16x32_bf16 v[8:11], v[170:173], v[210:213], v[8:11]
	v_mfma_f32_16x16x32_bf16 v[0:3], v[178:181], v[210:213], v[0:3]
	v_mfma_f32_16x16x32_bf16 v[56:59], v[174:177], v[190:193], v[56:59]
	v_mfma_f32_16x16x32_bf16 v[48:51], v[182:185], v[190:193], v[48:51]
	v_mfma_f32_16x16x32_bf16 v[40:43], v[174:177], v[198:201], v[40:43]
	v_mfma_f32_16x16x32_bf16 v[32:35], v[182:185], v[198:201], v[32:35]
	v_mfma_f32_16x16x32_bf16 v[24:27], v[174:177], v[206:209], v[24:27]
	v_mfma_f32_16x16x32_bf16 v[16:19], v[182:185], v[206:209], v[16:19]
	v_mfma_f32_16x16x32_bf16 v[8:11], v[174:177], v[214:217], v[8:11]
	v_mfma_f32_16x16x32_bf16 v[0:3], v[182:185], v[214:217], v[0:3]
	s_setprio 0
	s_barrier
	s_add_i32 s33, 0, 0x18000
	v_add_u32_e32 v153, s33, v145
	s_add_i32 s34, 0, 0x1c000
	ds_read_b128 v[154:157], v153
	ds_read_b128 v[158:161], v153 offset:1024
	ds_read_b128 v[162:165], v153 offset:2048
	ds_read_b128 v[166:169], v153 offset:3072
	v_add_u32_e32 v153, s34, v145
	ds_read_b128 v[170:173], v153
	ds_read_b128 v[174:177], v153 offset:1024
	ds_read_b128 v[178:181], v153 offset:2048
	ds_read_b128 v[182:185], v153 offset:3072
	s_add_u32 s44, s44, 0x40000
	s_addc_u32 s45, s45, 0
	s_mov_b32 m0, s56
	v_lshl_add_u64 v[224:225], s[44:45], 0, v[128:129]
	ds_read_b128 v[186:189], v149 offset:32768
	ds_read_b128 v[190:193], v149 offset:33792
	ds_read_b128 v[194:197], v149 offset:34816
	ds_read_b128 v[198:201], v149 offset:35840
	ds_read_b128 v[202:205], v149 offset:36864
	ds_read_b128 v[206:209], v149 offset:37888
	ds_read_b128 v[210:213], v149 offset:38912
	ds_read_b128 v[214:217], v149 offset:39936
	global_load_lds_dwordx4 v[224:225], off
	v_lshl_add_u64 v[224:225], s[44:45], 0, v[132:133]
	s_mov_b32 m0, s57
	s_nop 0
	global_load_lds_dwordx4 v[224:225], off
	s_cmp_eq_u32 s77, 2
	s_cbranch_scc1 .Lds7_2_a
	s_cmp_eq_u32 s77, 7
	s_cbranch_scc1 .Lds7_2_b
	s_waitcnt vmcnt(8)
; #define PG8_STAGE(bufoff, gbase, voff) do { _Pragma("unroll") for (int _i = 0; _i < 2; ++_i) \
;         __builtin_amdgcn_global_load_lds((const unsigned*)((const char*)(gbase) + (voff)[_i]), (PG8_LAS unsigned*)(lds + (bufoff) + ldsw + _i * 8192), 16, 0, 0); } while (0)
; #define PG8_LDA(dst, b, h) do { _Pragma("unroll") for (int m = 0; m < 4; ++m) _Pragma("unroll") for (int k = 0; k < 2; ++k) dst[m][k] = *(const PG8_LAS bf16x8*)(lds + PG8_SA(b, h) + aoff + m * 2048 + k * 1024); } while (0)
; #define PG8_LDB(dst, b, h) do { _Pragma("unroll") for (int n = 0; n < 2; ++n) _Pragma("unroll") for (int k = 0; k < 2; ++k) dst[n][k] = *(const PG8_LAS bf16x8*)(lds + PG8_SB(b, h) + boff + n * 2048 + k * 1024); } while (0)
; template <class Epi, class Sched, bool ALIGN_EPI = false, bool SP2 = false>
; __device__ __forceinline__ void gemm_phase(PG8_LAS unsigned char* lds, const Gemm g, const Sched& S, const Epi& E) {
;     ...
;         for (int t = 0; t < nt; t += 2) {
;             const bool last = (t == nt - 2);
;             const char* a1 = cA + (size_t)(t + 1) * kstep;
;             const char* a2 = last ? nA : cA + (size_t)(t + 2) * kstep; const char* b2 = last ? nB : cB + (size_t)(t + 2) * kstep;
;             const char* a3 = a2 + kstep; const char* b3 = b2 + kstep;
;             if (last && has_next) S.a_ready(nxt);
;             if constexpr (SP2) {
;             PG8_LDB(B0, 0, 0); PG8_LDB(B1, 0, 1); PG8_SCHED; PG8_LDA(At, 0, 0); PG8_STAGE(PG8_SA(1, 1), a1 + hstep, voffA);
;             PG8_WAIT_V(8); PG8_WAIT_L(0); PG8_BAR; PG8_MMA(0, 0, At, B0); PG8_MMA(0, 1, At, B1); PG8_BAR; PG8_SCHED;
;             PG8_LDA(At, 0, 1); PG8_STAGE(PG8_SB(0, 0), b2, voffB); PG8_STAGE(PG8_SB(0, 1), b2 + hstep, voffB); PG8_STAGE(PG8_SA(0, 0), a2, voffA);
;             PG8_WAIT_V(8); PG8_WAIT_L(0); PG8_BAR; PG8_MMA(1, 0, At, B0); PG8_MMA(1, 1, At, B1); PG8_BAR; PG8_SCHED;
;             PG8_LDB(B0, 1, 0); PG8_LDB(B1, 1, 1); PG8_SCHED; PG8_LDA(At, 1, 0); PG8_STAGE(PG8_SA(0, 1), a2 + hstep, voffA);
;             PG8_WAIT_V(8); PG8_WAIT_L(0); PG8_BAR; PG8_MMA(0, 0, At, B0); PG8_MMA(0, 1, At, B1); PG8_BAR; PG8_SCHED;
;             PG8_LDA(At, 1, 1); PG8_STAGE(PG8_SB(1, 0), b3, voffB); PG8_STAGE(PG8_SB(1, 1), b3 + hstep, voffB); PG8_STAGE(PG8_SA(1, 0), a3, voffA);
;             PG8_WAIT_V(8); PG8_WAIT_L(0); PG8_BAR; PG8_MMA(1, 0, At, B0); PG8_MMA(1, 1, At, B1); PG8_BAR; PG8_SCHED;
.Lds7_2_ret:
	s_waitcnt lgkmcnt(0)
	s_barrier
	s_setprio 1
	s_waitcnt lgkmcnt(0)
	v_mfma_f32_16x16x32_bf16 v[124:127], v[154:157], v[186:189], v[124:127]
	v_mfma_f32_16x16x32_bf16 v[116:119], v[162:165], v[186:189], v[116:119]
	v_mfma_f32_16x16x32_bf16 v[108:111], v[154:157], v[194:197], v[108:111]
	v_mfma_f32_16x16x32_bf16 v[100:103], v[162:165], v[194:197], v[100:103]
	v_mfma_f32_16x16x32_bf16 v[92:95], v[154:157], v[202:205], v[92:95]
	v_mfma_f32_16x16x32_bf16 v[84:87], v[162:165], v[202:205], v[84:87]
	v_mfma_f32_16x16x32_bf16 v[76:79], v[154:157], v[210:213], v[76:79]
	v_mfma_f32_16x16x32_bf16 v[68:71], v[162:165], v[210:213], v[68:71]
	v_mfma_f32_16x16x32_bf16 v[124:127], v[158:161], v[190:193], v[124:127]
	v_mfma_f32_16x16x32_bf16 v[116:119], v[166:169], v[190:193], v[116:119]
	v_mfma_f32_16x16x32_bf16 v[108:111], v[158:161], v[198:201], v[108:111]
	v_mfma_f32_16x16x32_bf16 v[100:103], v[166:169], v[198:201], v[100:103]
	v_mfma_f32_16x16x32_bf16 v[92:95], v[158:161], v[206:209], v[92:95]
	v_mfma_f32_16x16x32_bf16 v[84:87], v[166:169], v[206:209], v[84:87]
	v_mfma_f32_16x16x32_bf16 v[76:79], v[158:161], v[214:217], v[76:79]
	v_mfma_f32_16x16x32_bf16 v[68:71], v[166:169], v[214:217], v[68:71]
	s_setprio 0
	s_setprio 1
	v_mfma_f32_16x16x32_bf16 v[120:123], v[170:173], v[186:189], v[120:123]
	v_mfma_f32_16x16x32_bf16 v[112:115], v[178:181], v[186:189], v[112:115]
	v_mfma_f32_16x16x32_bf16 v[104:107], v[170:173], v[194:197], v[104:107]
	v_mfma_f32_16x16x32_bf16 v[96:99], v[178:181], v[194:197], v[96:99]
	v_mfma_f32_16x16x32_bf16 v[88:91], v[170:173], v[202:205], v[88:91]
	v_mfma_f32_16x16x32_bf16 v[80:83], v[178:181], v[202:205], v[80:83]
	v_mfma_f32_16x16x32_bf16 v[72:75], v[170:173], v[210:213], v[72:75]
	v_mfma_f32_16x16x32_bf16 v[64:67], v[178:181], v[210:213], v[64:67]
	v_mfma_f32_16x16x32_bf16 v[120:123], v[174:177], v[190:193], v[120:123]
	v_mfma_f32_16x16x32_bf16 v[112:115], v[182:185], v[190:193], v[112:115]
	v_mfma_f32_16x16x32_bf16 v[104:107], v[174:177], v[198:201], v[104:107]
	v_mfma_f32_16x16x32_bf16 v[96:99], v[182:185], v[198:201], v[96:99]
	v_mfma_f32_16x16x32_bf16 v[88:91], v[174:177], v[206:209], v[88:91]
	v_mfma_f32_16x16x32_bf16 v[80:83], v[182:185], v[206:209], v[80:83]
	v_mfma_f32_16x16x32_bf16 v[72:75], v[174:177], v[214:217], v[72:75]
	v_mfma_f32_16x16x32_bf16 v[64:67], v[182:185], v[214:217], v[64:67]
	s_setprio 0
	s_barrier
	s_add_i32 s33, s33, s52
	v_lshl_add_u64 v[150:151], v[150:151], 0, s[10:11]
	s_mov_b32 m0, s33
	ds_read_b128 v[186:189], v149 offset:49152
	ds_read_b128 v[190:193], v149 offset:50176
	ds_read_b128 v[194:197], v149 offset:51200
	ds_read_b128 v[198:201], v149 offset:52224
	ds_read_b128 v[202:205], v149 offset:53248
	ds_read_b128 v[206:209], v149 offset:54272
	ds_read_b128 v[210:213], v149 offset:55296
	ds_read_b128 v[214:217], v149 offset:56320
	global_load_lds_dwordx4 v[150:151], off
	s_add_i32 m0, s33, 0x2000
	s_add_u32 s42, s42, 0x40080
	v_lshl_add_u64 v[150:151], v[218:219], 0, s[10:11]
	s_addc_u32 s43, s43, 0
	s_add_i32 s33, s34, s52
	global_load_lds_dwordx4 v[150:151], off
	v_lshl_add_u64 v[150:151], s[42:43], 0, v[130:131]
	s_mov_b32 m0, s33
	s_nop 0
	global_load_lds_dwordx4 v[150:151], off
	v_lshl_add_u64 v[150:151], s[42:43], 0, v[134:135]
	s_add_i32 m0, s33, 0x2000
	s_nop 0
	global_load_lds_dwordx4 v[150:151], off
	v_lshl_add_u64 v[150:151], v[220:221], 0, s[10:11]
	s_mov_b32 m0, s60
	s_nop 0
	global_load_lds_dwordx4 v[150:151], off
	v_lshl_add_u64 v[150:151], v[222:223], 0, s[10:11]
	s_mov_b32 m0, s61
	s_nop 0
	global_load_lds_dwordx4 v[150:151], off
	s_cmp_eq_u32 s77, 3
	s_cbranch_scc1 .Lds7_3_a
	s_cmp_eq_u32 s77, 8
	s_cbranch_scc1 .Lds7_3_b
	s_waitcnt vmcnt(8)
.Lds7_3_ret:
	s_waitcnt lgkmcnt(0)
	s_barrier
	s_setprio 1
	s_waitcnt lgkmcnt(0)
	v_mfma_f32_16x16x32_bf16 v[60:63], v[154:157], v[186:189], v[60:63]
	v_mfma_f32_16x16x32_bf16 v[52:55], v[162:165], v[186:189], v[52:55]
	v_mfma_f32_16x16x32_bf16 v[44:47], v[154:157], v[194:197], v[44:47]
	v_mfma_f32_16x16x32_bf16 v[36:39], v[162:165], v[194:197], v[36:39]
	v_mfma_f32_16x16x32_bf16 v[28:31], v[154:157], v[202:205], v[28:31]
	v_mfma_f32_16x16x32_bf16 v[20:23], v[162:165], v[202:205], v[20:23]
	v_mfma_f32_16x16x32_bf16 v[12:15], v[154:157], v[210:213], v[12:15]
	v_mfma_f32_16x16x32_bf16 v[4:7], v[162:165], v[210:213], v[4:7]
	v_mfma_f32_16x16x32_bf16 v[60:63], v[158:161], v[190:193], v[60:63]
	v_mfma_f32_16x16x32_bf16 v[52:55], v[166:169], v[190:193], v[52:55]
	v_mfma_f32_16x16x32_bf16 v[44:47], v[158:161], v[198:201], v[44:47]
	v_mfma_f32_16x16x32_bf16 v[36:39], v[166:169], v[198:201], v[36:39]
	v_mfma_f32_16x16x32_bf16 v[28:31], v[158:161], v[206:209], v[28:31]
	v_mfma_f32_16x16x32_bf16 v[20:23], v[166:169], v[206:209], v[20:23]
	v_mfma_f32_16x16x32_bf16 v[12:15], v[158:161], v[214:217], v[12:15]
	v_mfma_f32_16x16x32_bf16 v[4:7], v[166:169], v[214:217], v[4:7]
	s_setprio 0
	s_setprio 1
	v_mfma_f32_16x16x32_bf16 v[56:59], v[170:173], v[186:189], v[56:59]
	v_mfma_f32_16x16x32_bf16 v[48:51], v[178:181], v[186:189], v[48:51]
	v_mfma_f32_16x16x32_bf16 v[40:43], v[170:173], v[194:197], v[40:43]
	v_mfma_f32_16x16x32_bf16 v[32:35], v[178:181], v[194:197], v[32:35]
	v_mfma_f32_16x16x32_bf16 v[24:27], v[170:173], v[202:205], v[24:27]
	v_mfma_f32_16x16x32_bf16 v[16:19], v[178:181], v[202:205], v[16:19]
	v_mfma_f32_16x16x32_bf16 v[8:11], v[170:173], v[210:213], v[8:11]
	v_mfma_f32_16x16x32_bf16 v[0:3], v[178:181], v[210:213], v[0:3]
	v_mfma_f32_16x16x32_bf16 v[56:59], v[174:177], v[190:193], v[56:59]
	v_mfma_f32_16x16x32_bf16 v[48:51], v[182:185], v[190:193], v[48:51]
	v_mfma_f32_16x16x32_bf16 v[40:43], v[174:177], v[198:201], v[40:43]
	v_mfma_f32_16x16x32_bf16 v[32:35], v[182:185], v[198:201], v[32:35]
	v_mfma_f32_16x16x32_bf16 v[24:27], v[174:177], v[206:209], v[24:27]
	v_mfma_f32_16x16x32_bf16 v[16:19], v[182:185], v[206:209], v[16:19]
	v_mfma_f32_16x16x32_bf16 v[8:11], v[174:177], v[214:217], v[8:11]
	v_mfma_f32_16x16x32_bf16 v[0:3], v[182:185], v[214:217], v[0:3]
	s_setprio 0
	s_barrier
	s_add_i32 s76, s76, 2
	s_add_u32 s40, s40, 0x100
	s_addc_u32 s41, s41, 0
	s_add_u32 s74, s74, 0x100
	s_addc_u32 s75, s75, 0
	s_cmp_gt_u32 s76, 13
	s_cbranch_scc0 .LBB0_714
	s_and_b64 vcc, exec, s[12:13]
	s_cbranch_vccz .LBB0_717
	s_barrier

; __device__ __forceinline__ unsigned pk2(float lo, float hi) { f32x2 v = {lo, hi}; bf16x2_t b = __builtin_convertvector(v, bf16x2_t); return __builtin_bit_cast(unsigned, b); }
; __device__ __forceinline__ float silu_f(float a) { return a * __builtin_amdgcn_rcpf(1.0f + __expf(-a)); }
; #define PG8_WAIT_V(n) asm volatile("s_waitcnt vmcnt(" #n ")" ::: "memory")
; #define PG8_WAIT_L(n) asm volatile("s_waitcnt lgkmcnt(" #n ")" ::: "memory")
; #define PG8_BAR __builtin_amdgcn_s_barrier()
;     __device__ __forceinline__ void operator()(const f32x4 (&acc)[2][2][4][2], const Unit& u, int wr, int wc, int fr, int fq) const {
;     ...
;             for (int m = 0; m < 4; ++m) { const int row = row0 + ai * HALF + m * 16;
;                 const f32x4 a0 = acc[ai][0][m][0], a1 = acc[ai][0][m][1], b0 = acc[ai][1][m][0], b1 = acc[ai][1][m][1];
;                 u32x4 w; w.x = pk2(silu_f(a0[0]) * b0[0], silu_f(a0[1]) * b0[1]); w.y = pk2(silu_f(a0[2]) * b0[2], silu_f(a0[3]) * b0[3]);
;                 w.z = pk2(silu_f(a1[0]) * b1[0], silu_f(a1[1]) * b1[1]); w.w = pk2(silu_f(a1[2]) * b1[2], silu_f(a1[3]) * b1[3]);
;                 *(u32x4*)(H + (size_t)row * ldh + col0) = w; }
; template <class Epi, class Sched, bool ALIGN_EPI = false, bool SP2 = false>
; __device__ __forceinline__ void gemm_phase(PG8_LAS unsigned char* lds, const Gemm g, const Sched& S, const Epi& E) {
;     ...
;             PG8_LDB(B0, 0, 0); PG8_LDB(B1, 0, 1); PG8_SCHED; PG8_LDA(At, 0, 0); PG8_STAGE(PG8_SA(1, 1), a1 + hstep, voffA);
;             PG8_WAIT_V(8); PG8_WAIT_L(0); PG8_BAR; PG8_MMA(0, 0, At, B0); PG8_MMA(0, 1, At, B1); PG8_BAR; PG8_SCHED;
;             PG8_LDA(At, 0, 1); PG8_STAGE(PG8_SB(0, 0), b2, voffB); PG8_STAGE(PG8_SB(0, 1), b2 + hstep, voffB); PG8_STAGE(PG8_SA(0, 0), a2, voffA);
;             PG8_WAIT_V(8); PG8_WAIT_L(0); PG8_BAR; PG8_MMA(1, 0, At, B0); PG8_MMA(1, 1, At, B1); PG8_BAR; PG8_SCHED;
;             PG8_LDB(B0, 1, 0); PG8_LDB(B1, 1, 1); PG8_SCHED; PG8_LDA(At, 1, 0); PG8_STAGE(PG8_SA(0, 1), a2 + hstep, voffA);
;             PG8_WAIT_V(8); PG8_WAIT_L(0); PG8_BAR; PG8_MMA(0, 0, At, B0); PG8_MMA(0, 1, At, B1); PG8_BAR; PG8_SCHED;
;             PG8_LDA(At, 1, 1); PG8_STAGE(PG8_SB(1, 0), b3, voffB); PG8_STAGE(PG8_SB(1, 1), b3 + hstep, voffB); PG8_STAGE(PG8_SA(1, 0), a3, voffA);
;             PG8_WAIT_V(8); PG8_WAIT_L(0); PG8_BAR; PG8_MMA(1, 0, At, B0); PG8_MMA(1, 1, At, B1); PG8_BAR; PG8_SCHED;
.Lds7_0_a:
	s_add_u32 s82, s8, 0x2c000
	s_addc_u32 s83, s9, 0
	global_store_dwordx4 v229, v[230:233], s[82:83]
	s_mov_b32 s77, 1
	s_waitcnt vmcnt(9)
	s_branch .Lds7_0_ret
.Lds7_0_b:
	s_add_u32 s82, s8, 0xdc000
	s_addc_u32 s83, s9, 0
	global_store_dwordx4 v229, v[246:249], s[82:83]
	s_mov_b32 s77, 5
	s_waitcnt vmcnt(11)
	s_branch .Lds7_0_ret
.Lds7_1_a:
	s_add_u32 s82, s8, 0x42000
	s_addc_u32 s83, s9, 0
	global_store_dwordx4 v229, v[234:237], s[82:83]
	s_mov_b32 s77, 2
	s_waitcnt vmcnt(10)
	s_branch .Lds7_1_ret
.Lds7_1_b:
	s_add_u32 s82, s8, 0xf2000
	s_addc_u32 s83, s9, 0
	global_store_dwordx4 v229, v[250:253], s[82:83]
	s_mov_b32 s77, 7
	s_waitcnt vmcnt(11)
	s_branch .Lds7_1_ret
.Lds7_2_a:
	s_add_u32 s82, s8, 0xb0000
	s_addc_u32 s83, s9, 0
	global_store_dwordx4 v229, v[238:241], s[82:83]
	s_mov_b32 s77, 3
	s_waitcnt vmcnt(11)
	s_branch .Lds7_2_ret
.Lds7_2_b:
	s_mov_b32 s77, 8
	s_waitcnt vmcnt(10)
	s_branch .Lds7_2_ret
.Lds7_3_a:
	s_add_u32 s82, s8, 0xc6000
	s_addc_u32 s83, s9, 0
	global_store_dwordx4 v229, v[242:245], s[82:83]
	s_mov_b32 s77, 4
	s_waitcnt vmcnt(11)
	s_branch .Lds7_3_ret
.Lds7_3_b:
	s_mov_b32 s77, 6
	s_waitcnt vmcnt(9)
	s_branch .Lds7_3_ret

; #define PG8_STAGE(bufoff, gbase, voff) do { _Pragma("unroll") for (int _i = 0; _i < 2; ++_i) \
;         __builtin_amdgcn_global_load_lds((const unsigned*)((const char*)(gbase) + (voff)[_i]), (PG8_LAS unsigned*)(lds + (bufoff) + ldsw + _i * 8192), 16, 0, 0); } while (0)
; #define PG8_LDA(dst, b, h) do { _Pragma("unroll") for (int m = 0; m < 4; ++m) _Pragma("unroll") for (int k = 0; k < 2; ++k) dst[m][k] = *(const PG8_LAS bf16x8*)(lds + PG8_SA(b, h) + aoff + m * 2048 + k * 1024); } while (0)
; #define PG8_LDB(dst, b, h) do { _Pragma("unroll") for (int n = 0; n < 2; ++n) _Pragma("unroll") for (int k = 0; k < 2; ++k) dst[n][k] = *(const PG8_LAS bf16x8*)(lds + PG8_SB(b, h) + boff + n * 2048 + k * 1024); } while (0)
; #define PG8_MMA(ai, bj, At, Bt) do { __builtin_amdgcn_s_setprio(1); _Pragma("unroll") for (int m = 0; m < 4; ++m) _Pragma("unroll") for (int n = 0; n < 2; ++n) _Pragma("unroll") for (int k = 0; k < 2; ++k) \
;         acc[ai][bj][m][n] = __builtin_amdgcn_mfma_f32_16x16x32_bf16(Bt[n][k], At[m][k], acc[ai][bj][m][n], 0, 0, 0); __builtin_amdgcn_s_setprio(0); } while (0)
; #define PG8_WAIT_V(n) asm volatile("s_waitcnt vmcnt(" #n ")" ::: "memory")
; #define PG8_BAR __builtin_amdgcn_s_barrier()
; template <class Epi, class Sched, bool ALIGN_EPI = false, bool SP2 = false>
; __device__ __forceinline__ void gemm_phase(PG8_LAS unsigned char* lds, const Gemm g, const Sched& S, const Epi& E) {
;     ...
;         for (int t = 0; t < nt; t += 2) {
;             const bool last = (t == nt - 2);
;             const char* a1 = cA + (size_t)(t + 1) * kstep;
;             const char* a2 = last ? nA : cA + (size_t)(t + 2) * kstep; const char* b2 = last ? nB : cB + (size_t)(t + 2) * kstep;
;             const char* a3 = a2 + kstep; const char* b3 = b2 + kstep;
;             if (last && has_next) S.a_ready(nxt);
;             if constexpr (SP2) {
;             PG8_LDB(B0, 0, 0); PG8_LDB(B1, 0, 1); PG8_SCHED; PG8_LDA(At, 0, 0); PG8_STAGE(PG8_SA(1, 1), a1 + hstep, voffA);
;             PG8_WAIT_V(8); PG8_WAIT_L(0); PG8_BAR; PG8_MMA(0, 0, At, B0); PG8_MMA(0, 1, At, B1); PG8_BAR; PG8_SCHED;
;             PG8_LDA(At, 0, 1); PG8_STAGE(PG8_SB(0, 0), b2, voffB); PG8_STAGE(PG8_SB(0, 1), b2 + hstep, voffB); PG8_STAGE(PG8_SA(0, 0), a2, voffA);
;             PG8_WAIT_V(8); PG8_WAIT_L(0); PG8_BAR; PG8_MMA(1, 0, At, B0); PG8_MMA(1, 1, At, B1); PG8_BAR; PG8_SCHED;
.LBB0_1342:
	ds_read_b128 v[154:157], v147
	ds_read_b128 v[158:161], v147 offset:1024
	ds_read_b128 v[162:165], v147 offset:2048
	ds_read_b128 v[166:169], v147 offset:3072
	ds_read_b128 v[170:173], v148
	ds_read_b128 v[174:177], v148 offset:1024
	ds_read_b128 v[178:181], v148 offset:2048
	ds_read_b128 v[182:185], v148 offset:3072
	s_add_u32 s33, s36, 0xfffc0080
	s_addc_u32 s34, s37, -1
	s_cmp_eq_u32 s62, 12
	s_cselect_b32 s41, s19, s34
	s_cselect_b32 s40, s58, s33
	s_cselect_b32 s39, s15, s61
	s_cselect_b32 s38, s59, s60
	v_lshl_add_u64 v[150:151], s[36:37], 0, v[136:137]
	s_add_i32 m0, s25, 0xc000
	ds_read_b128 v[186:189], v149
	ds_read_b128 v[190:193], v149 offset:1024
	ds_read_b128 v[194:197], v149 offset:2048
	ds_read_b128 v[198:201], v149 offset:3072
	ds_read_b128 v[202:205], v149 offset:4096
	ds_read_b128 v[206:209], v149 offset:5120
	ds_read_b128 v[210:213], v149 offset:6144
	ds_read_b128 v[214:217], v149 offset:7168
	global_load_lds_dwordx4 v[150:151], off
	v_lshl_add_u64 v[150:151], s[36:37], 0, v[138:139]
	s_add_i32 m0, s25, 0xe000
	s_nop 0
	global_load_lds_dwordx4 v[150:151], off
	s_cmp_eq_u32 s77, 0
	s_cbranch_scc1 .Lds15_0_a
	s_cmp_eq_u32 s77, 4
	s_cbranch_scc1 .Lds15_0_b
	s_waitcnt vmcnt(8)
.Lds15_0_ret:
	s_waitcnt lgkmcnt(0)
	s_barrier
	s_setprio 1
	s_waitcnt lgkmcnt(0)
	v_mfma_f32_16x16x32_bf16 v[124:127], v[154:157], v[186:189], v[124:127]
	v_mfma_f32_16x16x32_bf16 v[116:119], v[162:165], v[186:189], v[116:119]
	v_mfma_f32_16x16x32_bf16 v[108:111], v[154:157], v[194:197], v[108:111]
	v_mfma_f32_16x16x32_bf16 v[100:103], v[162:165], v[194:197], v[100:103]
	v_mfma_f32_16x16x32_bf16 v[92:95], v[154:157], v[202:205], v[92:95]
	v_mfma_f32_16x16x32_bf16 v[84:87], v[162:165], v[202:205], v[84:87]
	v_mfma_f32_16x16x32_bf16 v[76:79], v[154:157], v[210:213], v[76:79]
	v_mfma_f32_16x16x32_bf16 v[68:71], v[162:165], v[210:213], v[68:71]
	v_mfma_f32_16x16x32_bf16 v[124:127], v[158:161], v[190:193], v[124:127]
	v_mfma_f32_16x16x32_bf16 v[116:119], v[166:169], v[190:193], v[116:119]
	v_mfma_f32_16x16x32_bf16 v[108:111], v[158:161], v[198:201], v[108:111]
	v_mfma_f32_16x16x32_bf16 v[100:103], v[166:169], v[198:201], v[100:103]
	v_mfma_f32_16x16x32_bf16 v[92:95], v[158:161], v[206:209], v[92:95]
	v_mfma_f32_16x16x32_bf16 v[84:87], v[166:169], v[206:209], v[84:87]
	v_mfma_f32_16x16x32_bf16 v[76:79], v[158:161], v[214:217], v[76:79]
	v_mfma_f32_16x16x32_bf16 v[68:71], v[166:169], v[214:217], v[68:71]
	s_setprio 0
	s_setprio 1
	v_mfma_f32_16x16x32_bf16 v[120:123], v[170:173], v[186:189], v[120:123]
	v_mfma_f32_16x16x32_bf16 v[112:115], v[178:181], v[186:189], v[112:115]
	v_mfma_f32_16x16x32_bf16 v[104:107], v[170:173], v[194:197], v[104:107]
	v_mfma_f32_16x16x32_bf16 v[96:99], v[178:181], v[194:197], v[96:99]
	v_mfma_f32_16x16x32_bf16 v[88:91], v[170:173], v[202:205], v[88:91]
	v_mfma_f32_16x16x32_bf16 v[80:83], v[178:181], v[202:205], v[80:83]
	v_mfma_f32_16x16x32_bf16 v[72:75], v[170:173], v[210:213], v[72:75]
	v_mfma_f32_16x16x32_bf16 v[64:67], v[178:181], v[210:213], v[64:67]
	v_mfma_f32_16x16x32_bf16 v[120:123], v[174:177], v[190:193], v[120:123]
	v_mfma_f32_16x16x32_bf16 v[112:115], v[182:185], v[190:193], v[112:115]
	v_mfma_f32_16x16x32_bf16 v[104:107], v[174:177], v[198:201], v[104:107]
	v_mfma_f32_16x16x32_bf16 v[96:99], v[182:185], v[198:201], v[96:99]
	v_mfma_f32_16x16x32_bf16 v[88:91], v[174:177], v[206:209], v[88:91]
	v_mfma_f32_16x16x32_bf16 v[80:83], v[182:185], v[206:209], v[80:83]
	v_mfma_f32_16x16x32_bf16 v[72:75], v[174:177], v[214:217], v[72:75]
	v_mfma_f32_16x16x32_bf16 v[64:67], v[182:185], v[214:217], v[64:67]
	s_setprio 0
	s_barrier
	s_add_i32 s33, s54, s44
	v_lshl_add_u64 v[150:151], s[38:39], 0, v[130:131]
	s_mov_b32 m0, s33
	ds_read_b128 v[186:189], v149 offset:16384
	ds_read_b128 v[190:193], v149 offset:17408
	ds_read_b128 v[194:197], v149 offset:18432
	ds_read_b128 v[198:201], v149 offset:19456
	ds_read_b128 v[202:205], v149 offset:20480
	ds_read_b128 v[206:209], v149 offset:21504
	ds_read_b128 v[210:213], v149 offset:22528
	ds_read_b128 v[214:217], v149 offset:23552
	global_load_lds_dwordx4 v[150:151], off
	s_add_i32 m0, s33, 0x2000
	s_add_u32 s64, s38, 0x40000
	v_lshl_add_u64 v[218:219], s[38:39], 0, v[134:135]
	s_addc_u32 s65, s39, 0
	s_add_i32 s33, s55, s44
	global_load_lds_dwordx4 v[218:219], off
	v_lshl_add_u64 v[220:221], s[64:65], 0, v[130:131]
	s_mov_b32 m0, s33
	v_lshl_add_u64 v[222:223], s[40:41], 0, v[132:133]
	global_load_lds_dwordx4 v[220:221], off
	v_lshl_add_u64 v[220:221], s[64:65], 0, v[134:135]
	s_add_i32 m0, s33, 0x2000
	s_nop 0
	global_load_lds_dwordx4 v[220:221], off
	v_lshl_add_u64 v[220:221], s[40:41], 0, v[128:129]
	s_mov_b32 m0, s25
	s_nop 0
	global_load_lds_dwordx4 v[220:221], off
	s_mov_b32 m0, s47
	s_nop 0
	global_load_lds_dwordx4 v[222:223], off
	s_cmp_eq_u32 s77, 1
	s_cbranch_scc1 .Lds15_1_a
	s_cmp_eq_u32 s77, 5
	s_cbranch_scc1 .Lds15_1_b
	s_waitcnt vmcnt(8)
; #define PG8_STAGE(bufoff, gbase, voff) do { _Pragma("unroll") for (int _i = 0; _i < 2; ++_i) \
;         __builtin_amdgcn_global_load_lds((const unsigned*)((const char*)(gbase) + (voff)[_i]), (PG8_LAS unsigned*)(lds + (bufoff) + ldsw + _i * 8192), 16, 0, 0); } while (0)
; #define PG8_LDA(dst, b, h) do { _Pragma("unroll") for (int m = 0; m < 4; ++m) _Pragma("unroll") for (int k = 0; k < 2; ++k) dst[m][k] = *(const PG8_LAS bf16x8*)(lds + PG8_SA(b, h) + aoff + m * 2048 + k * 1024); } while (0)
; #define PG8_LDB(dst, b, h) do { _Pragma("unroll") for (int n = 0; n < 2; ++n) _Pragma("unroll") for (int k = 0; k < 2; ++k) dst[n][k] = *(const PG8_LAS bf16x8*)(lds + PG8_SB(b, h) + boff + n * 2048 + k * 1024); } while (0)
; #define PG8_MMA(ai, bj, At, Bt) do { __builtin_amdgcn_s_setprio(1); _Pragma("unroll") for (int m = 0; m < 4; ++m) _Pragma("unroll") for (int n = 0; n < 2; ++n) _Pragma("unroll") for (int k = 0; k < 2; ++k) \
;         acc[ai][bj][m][n] = __builtin_amdgcn_mfma_f32_16x16x32_bf16(Bt[n][k], At[m][k], acc[ai][bj][m][n], 0, 0, 0); __builtin_amdgcn_s_setprio(0); } while (0)
; #define PG8_WAIT_V(n) asm volatile("s_waitcnt vmcnt(" #n ")" ::: "memory")
; #define PG8_WAIT_L(n) asm volatile("s_waitcnt lgkmcnt(" #n ")" ::: "memory")
; #define PG8_BAR __builtin_amdgcn_s_barrier()
; #define PG8_SCHED __builtin_amdgcn_sched_barrier(0)
; template <class Epi, class Sched, bool ALIGN_EPI = false, bool SP2 = false>
; __device__ __forceinline__ void gemm_phase(PG8_LAS unsigned char* lds, const Gemm g, const Sched& S, const Epi& E) {
;     ...
;             PG8_WAIT_V(8); PG8_WAIT_L(0); PG8_BAR; PG8_MMA(0, 0, At, B0); PG8_MMA(0, 1, At, B1); PG8_BAR; PG8_SCHED;
;             PG8_LDA(At, 0, 1); PG8_STAGE(PG8_SB(0, 0), b2, voffB); PG8_STAGE(PG8_SB(0, 1), b2 + hstep, voffB); PG8_STAGE(PG8_SA(0, 0), a2, voffA);
;             PG8_WAIT_V(8); PG8_WAIT_L(0); PG8_BAR; PG8_MMA(1, 0, At, B0); PG8_MMA(1, 1, At, B1); PG8_BAR; PG8_SCHED;
;             PG8_LDB(B0, 1, 0); PG8_LDB(B1, 1, 1); PG8_SCHED; PG8_LDA(At, 1, 0); PG8_STAGE(PG8_SA(0, 1), a2 + hstep, voffA);
.Lds15_1_ret:
	s_waitcnt lgkmcnt(0)
	s_barrier
	s_setprio 1
	s_waitcnt lgkmcnt(0)
	v_mfma_f32_16x16x32_bf16 v[60:63], v[154:157], v[186:189], v[60:63]
	v_mfma_f32_16x16x32_bf16 v[52:55], v[162:165], v[186:189], v[52:55]
	v_mfma_f32_16x16x32_bf16 v[44:47], v[154:157], v[194:197], v[44:47]
	v_mfma_f32_16x16x32_bf16 v[36:39], v[162:165], v[194:197], v[36:39]
	v_mfma_f32_16x16x32_bf16 v[28:31], v[154:157], v[202:205], v[28:31]
	v_mfma_f32_16x16x32_bf16 v[20:23], v[162:165], v[202:205], v[20:23]
	v_mfma_f32_16x16x32_bf16 v[12:15], v[154:157], v[210:213], v[12:15]
	v_mfma_f32_16x16x32_bf16 v[4:7], v[162:165], v[210:213], v[4:7]
	v_mfma_f32_16x16x32_bf16 v[60:63], v[158:161], v[190:193], v[60:63]
	v_mfma_f32_16x16x32_bf16 v[52:55], v[166:169], v[190:193], v[52:55]
	v_mfma_f32_16x16x32_bf16 v[44:47], v[158:161], v[198:201], v[44:47]
	v_mfma_f32_16x16x32_bf16 v[36:39], v[166:169], v[198:201], v[36:39]
	v_mfma_f32_16x16x32_bf16 v[28:31], v[158:161], v[206:209], v[28:31]
	v_mfma_f32_16x16x32_bf16 v[20:23], v[166:169], v[206:209], v[20:23]
	v_mfma_f32_16x16x32_bf16 v[12:15], v[158:161], v[214:217], v[12:15]
	v_mfma_f32_16x16x32_bf16 v[4:7], v[166:169], v[214:217], v[4:7]
	s_setprio 0
	s_setprio 1
	v_mfma_f32_16x16x32_bf16 v[56:59], v[170:173], v[186:189], v[56:59]
	v_mfma_f32_16x16x32_bf16 v[48:51], v[178:181], v[186:189], v[48:51]
	v_mfma_f32_16x16x32_bf16 v[40:43], v[170:173], v[194:197], v[40:43]
	v_mfma_f32_16x16x32_bf16 v[32:35], v[178:181], v[194:197], v[32:35]
	v_mfma_f32_16x16x32_bf16 v[24:27], v[170:173], v[202:205], v[24:27]
	v_mfma_f32_16x16x32_bf16 v[16:19], v[178:181], v[202:205], v[16:19]
	v_mfma_f32_16x16x32_bf16 v[8:11], v[170:173], v[210:213], v[8:11]
	v_mfma_f32_16x16x32_bf16 v[0:3], v[178:181], v[210:213], v[0:3]
	v_mfma_f32_16x16x32_bf16 v[56:59], v[174:177], v[190:193], v[56:59]
	v_mfma_f32_16x16x32_bf16 v[48:51], v[182:185], v[190:193], v[48:51]
	v_mfma_f32_16x16x32_bf16 v[40:43], v[174:177], v[198:201], v[40:43]
	v_mfma_f32_16x16x32_bf16 v[32:35], v[182:185], v[198:201], v[32:35]
	v_mfma_f32_16x16x32_bf16 v[24:27], v[174:177], v[206:209], v[24:27]
	v_mfma_f32_16x16x32_bf16 v[16:19], v[182:185], v[206:209], v[16:19]
	v_mfma_f32_16x16x32_bf16 v[8:11], v[174:177], v[214:217], v[8:11]
	v_mfma_f32_16x16x32_bf16 v[0:3], v[182:185], v[214:217], v[0:3]
	s_setprio 0
	s_barrier
	s_add_i32 s33, 0, 0x18000
	v_add_u32_e32 v153, s33, v145
	s_add_i32 s34, 0, 0x1c000
	ds_read_b128 v[154:157], v153
	ds_read_b128 v[158:161], v153 offset:1024
	ds_read_b128 v[162:165], v153 offset:2048
	ds_read_b128 v[166:169], v153 offset:3072
	v_add_u32_e32 v153, s34, v145
	ds_read_b128 v[170:173], v153
	ds_read_b128 v[174:177], v153 offset:1024
	ds_read_b128 v[178:181], v153 offset:2048
	ds_read_b128 v[182:185], v153 offset:3072
	s_add_u32 s40, s40, 0x40000
	s_addc_u32 s41, s41, 0
	s_mov_b32 m0, s48
	v_lshl_add_u64 v[224:225], s[40:41], 0, v[128:129]
	ds_read_b128 v[186:189], v149 offset:32768
	ds_read_b128 v[190:193], v149 offset:33792
	ds_read_b128 v[194:197], v149 offset:34816
	ds_read_b128 v[198:201], v149 offset:35840
	ds_read_b128 v[202:205], v149 offset:36864
	ds_read_b128 v[206:209], v149 offset:37888
	ds_read_b128 v[210:213], v149 offset:38912
	ds_read_b128 v[214:217], v149 offset:39936
	global_load_lds_dwordx4 v[224:225], off
	v_lshl_add_u64 v[224:225], s[40:41], 0, v[132:133]
	s_mov_b32 m0, s49
	s_nop 0
	global_load_lds_dwordx4 v[224:225], off
	s_cmp_eq_u32 s77, 2
	s_cbranch_scc1 .Lds15_2_a
	s_cmp_eq_u32 s77, 7
	s_cbranch_scc1 .Lds15_2_b
	s_waitcnt vmcnt(8)
; #define PG8_STAGE(bufoff, gbase, voff) do { _Pragma("unroll") for (int _i = 0; _i < 2; ++_i) \
;         __builtin_amdgcn_global_load_lds((const unsigned*)((const char*)(gbase) + (voff)[_i]), (PG8_LAS unsigned*)(lds + (bufoff) + ldsw + _i * 8192), 16, 0, 0); } while (0)
; #define PG8_LDA(dst, b, h) do { _Pragma("unroll") for (int m = 0; m < 4; ++m) _Pragma("unroll") for (int k = 0; k < 2; ++k) dst[m][k] = *(const PG8_LAS bf16x8*)(lds + PG8_SA(b, h) + aoff + m * 2048 + k * 1024); } while (0)
; #define PG8_LDB(dst, b, h) do { _Pragma("unroll") for (int n = 0; n < 2; ++n) _Pragma("unroll") for (int k = 0; k < 2; ++k) dst[n][k] = *(const PG8_LAS bf16x8*)(lds + PG8_SB(b, h) + boff + n * 2048 + k * 1024); } while (0)
; template <class Epi, class Sched, bool ALIGN_EPI = false, bool SP2 = false>
; __device__ __forceinline__ void gemm_phase(PG8_LAS unsigned char* lds, const Gemm g, const Sched& S, const Epi& E) {
;     ...
;         for (int t = 0; t < nt; t += 2) {
;             const bool last = (t == nt - 2);
;             const char* a1 = cA + (size_t)(t + 1) * kstep;
;             const char* a2 = last ? nA : cA + (size_t)(t + 2) * kstep; const char* b2 = last ? nB : cB + (size_t)(t + 2) * kstep;
;             const char* a3 = a2 + kstep; const char* b3 = b2 + kstep;
;             if (last && has_next) S.a_ready(nxt);
;             if constexpr (SP2) {
;             PG8_LDB(B0, 0, 0); PG8_LDB(B1, 0, 1); PG8_SCHED; PG8_LDA(At, 0, 0); PG8_STAGE(PG8_SA(1, 1), a1 + hstep, voffA);
;             PG8_WAIT_V(8); PG8_WAIT_L(0); PG8_BAR; PG8_MMA(0, 0, At, B0); PG8_MMA(0, 1, At, B1); PG8_BAR; PG8_SCHED;
;             PG8_LDA(At, 0, 1); PG8_STAGE(PG8_SB(0, 0), b2, voffB); PG8_STAGE(PG8_SB(0, 1), b2 + hstep, voffB); PG8_STAGE(PG8_SA(0, 0), a2, voffA);
;             PG8_WAIT_V(8); PG8_WAIT_L(0); PG8_BAR; PG8_MMA(1, 0, At, B0); PG8_MMA(1, 1, At, B1); PG8_BAR; PG8_SCHED;
;             PG8_LDB(B0, 1, 0); PG8_LDB(B1, 1, 1); PG8_SCHED; PG8_LDA(At, 1, 0); PG8_STAGE(PG8_SA(0, 1), a2 + hstep, voffA);
;             PG8_WAIT_V(8); PG8_WAIT_L(0); PG8_BAR; PG8_MMA(0, 0, At, B0); PG8_MMA(0, 1, At, B1); PG8_BAR; PG8_SCHED;
;             PG8_LDA(At, 1, 1); PG8_STAGE(PG8_SB(1, 0), b3, voffB); PG8_STAGE(PG8_SB(1, 1), b3 + hstep, voffB); PG8_STAGE(PG8_SA(1, 0), a3, voffA);
;             PG8_WAIT_V(8); PG8_WAIT_L(0); PG8_BAR; PG8_MMA(1, 0, At, B0); PG8_MMA(1, 1, At, B1); PG8_BAR; PG8_SCHED;
.Lds15_2_ret:
	s_waitcnt lgkmcnt(0)
	s_barrier
	s_setprio 1
	s_waitcnt lgkmcnt(0)
	v_mfma_f32_16x16x32_bf16 v[124:127], v[154:157], v[186:189], v[124:127]
	v_mfma_f32_16x16x32_bf16 v[116:119], v[162:165], v[186:189], v[116:119]
	v_mfma_f32_16x16x32_bf16 v[108:111], v[154:157], v[194:197], v[108:111]
	v_mfma_f32_16x16x32_bf16 v[100:103], v[162:165], v[194:197], v[100:103]
	v_mfma_f32_16x16x32_bf16 v[92:95], v[154:157], v[202:205], v[92:95]
	v_mfma_f32_16x16x32_bf16 v[84:87], v[162:165], v[202:205], v[84:87]
	v_mfma_f32_16x16x32_bf16 v[76:79], v[154:157], v[210:213], v[76:79]
	v_mfma_f32_16x16x32_bf16 v[68:71], v[162:165], v[210:213], v[68:71]
	v_mfma_f32_16x16x32_bf16 v[124:127], v[158:161], v[190:193], v[124:127]
	v_mfma_f32_16x16x32_bf16 v[116:119], v[166:169], v[190:193], v[116:119]
	v_mfma_f32_16x16x32_bf16 v[108:111], v[158:161], v[198:201], v[108:111]
	v_mfma_f32_16x16x32_bf16 v[100:103], v[166:169], v[198:201], v[100:103]
	v_mfma_f32_16x16x32_bf16 v[92:95], v[158:161], v[206:209], v[92:95]
	v_mfma_f32_16x16x32_bf16 v[84:87], v[166:169], v[206:209], v[84:87]
	v_mfma_f32_16x16x32_bf16 v[76:79], v[158:161], v[214:217], v[76:79]
	v_mfma_f32_16x16x32_bf16 v[68:71], v[166:169], v[214:217], v[68:71]
	s_setprio 0
	s_setprio 1
	v_mfma_f32_16x16x32_bf16 v[120:123], v[170:173], v[186:189], v[120:123]
	v_mfma_f32_16x16x32_bf16 v[112:115], v[178:181], v[186:189], v[112:115]
	v_mfma_f32_16x16x32_bf16 v[104:107], v[170:173], v[194:197], v[104:107]
	v_mfma_f32_16x16x32_bf16 v[96:99], v[178:181], v[194:197], v[96:99]
	v_mfma_f32_16x16x32_bf16 v[88:91], v[170:173], v[202:205], v[88:91]
	v_mfma_f32_16x16x32_bf16 v[80:83], v[178:181], v[202:205], v[80:83]
	v_mfma_f32_16x16x32_bf16 v[72:75], v[170:173], v[210:213], v[72:75]
	v_mfma_f32_16x16x32_bf16 v[64:67], v[178:181], v[210:213], v[64:67]
	v_mfma_f32_16x16x32_bf16 v[120:123], v[174:177], v[190:193], v[120:123]
	v_mfma_f32_16x16x32_bf16 v[112:115], v[182:185], v[190:193], v[112:115]
	v_mfma_f32_16x16x32_bf16 v[104:107], v[174:177], v[198:201], v[104:107]
	v_mfma_f32_16x16x32_bf16 v[96:99], v[182:185], v[198:201], v[96:99]
	v_mfma_f32_16x16x32_bf16 v[88:91], v[174:177], v[206:209], v[88:91]
	v_mfma_f32_16x16x32_bf16 v[80:83], v[182:185], v[206:209], v[80:83]
	v_mfma_f32_16x16x32_bf16 v[72:75], v[174:177], v[214:217], v[72:75]
	v_mfma_f32_16x16x32_bf16 v[64:67], v[182:185], v[214:217], v[64:67]
	s_setprio 0
	s_barrier
	s_add_i32 s33, s33, s44
	v_lshl_add_u64 v[150:151], v[150:151], 0, s[10:11]
	s_mov_b32 m0, s33
	ds_read_b128 v[186:189], v149 offset:49152
	ds_read_b128 v[190:193], v149 offset:50176
	ds_read_b128 v[194:197], v149 offset:51200
	ds_read_b128 v[198:201], v149 offset:52224
	ds_read_b128 v[202:205], v149 offset:53248
	ds_read_b128 v[206:209], v149 offset:54272
	ds_read_b128 v[210:213], v149 offset:55296
	ds_read_b128 v[214:217], v149 offset:56320
	global_load_lds_dwordx4 v[150:151], off
	s_add_i32 m0, s33, 0x2000
	s_add_u32 s38, s38, 0x40080
	v_lshl_add_u64 v[150:151], v[218:219], 0, s[10:11]
	s_addc_u32 s39, s39, 0
	s_add_i32 s33, s34, s44
	global_load_lds_dwordx4 v[150:151], off
	v_lshl_add_u64 v[150:151], s[38:39], 0, v[130:131]
	s_mov_b32 m0, s33
	s_nop 0
	global_load_lds_dwordx4 v[150:151], off
	v_lshl_add_u64 v[150:151], s[38:39], 0, v[134:135]
	s_add_i32 m0, s33, 0x2000
	s_nop 0
	global_load_lds_dwordx4 v[150:151], off
	v_lshl_add_u64 v[150:151], v[220:221], 0, s[10:11]
	s_mov_b32 m0, s52
	s_nop 0
	global_load_lds_dwordx4 v[150:151], off
	v_lshl_add_u64 v[150:151], v[222:223], 0, s[10:11]
	s_mov_b32 m0, s53
	s_nop 0
	global_load_lds_dwordx4 v[150:151], off
	s_cmp_eq_u32 s77, 3
	s_cbranch_scc1 .Lds15_3_a
	s_cmp_eq_u32 s77, 8
	s_cbranch_scc1 .Lds15_3_b
	s_waitcnt vmcnt(8)
.Lds15_3_ret:
	s_waitcnt lgkmcnt(0)
	s_barrier
	s_setprio 1
	s_waitcnt lgkmcnt(0)
	v_mfma_f32_16x16x32_bf16 v[60:63], v[154:157], v[186:189], v[60:63]
	v_mfma_f32_16x16x32_bf16 v[52:55], v[162:165], v[186:189], v[52:55]
	v_mfma_f32_16x16x32_bf16 v[44:47], v[154:157], v[194:197], v[44:47]
	v_mfma_f32_16x16x32_bf16 v[36:39], v[162:165], v[194:197], v[36:39]
	v_mfma_f32_16x16x32_bf16 v[28:31], v[154:157], v[202:205], v[28:31]
	v_mfma_f32_16x16x32_bf16 v[20:23], v[162:165], v[202:205], v[20:23]
	v_mfma_f32_16x16x32_bf16 v[12:15], v[154:157], v[210:213], v[12:15]
	v_mfma_f32_16x16x32_bf16 v[4:7], v[162:165], v[210:213], v[4:7]
	v_mfma_f32_16x16x32_bf16 v[60:63], v[158:161], v[190:193], v[60:63]
	v_mfma_f32_16x16x32_bf16 v[52:55], v[166:169], v[190:193], v[52:55]
	v_mfma_f32_16x16x32_bf16 v[44:47], v[158:161], v[198:201], v[44:47]
	v_mfma_f32_16x16x32_bf16 v[36:39], v[166:169], v[198:201], v[36:39]
	v_mfma_f32_16x16x32_bf16 v[28:31], v[158:161], v[206:209], v[28:31]
	v_mfma_f32_16x16x32_bf16 v[20:23], v[166:169], v[206:209], v[20:23]
	v_mfma_f32_16x16x32_bf16 v[12:15], v[158:161], v[214:217], v[12:15]
	v_mfma_f32_16x16x32_bf16 v[4:7], v[166:169], v[214:217], v[4:7]
	s_setprio 0
	s_setprio 1
	v_mfma_f32_16x16x32_bf16 v[56:59], v[170:173], v[186:189], v[56:59]
	v_mfma_f32_16x16x32_bf16 v[48:51], v[178:181], v[186:189], v[48:51]
	v_mfma_f32_16x16x32_bf16 v[40:43], v[170:173], v[194:197], v[40:43]
	v_mfma_f32_16x16x32_bf16 v[32:35], v[178:181], v[194:197], v[32:35]
	v_mfma_f32_16x16x32_bf16 v[24:27], v[170:173], v[202:205], v[24:27]
	v_mfma_f32_16x16x32_bf16 v[16:19], v[178:181], v[202:205], v[16:19]
	v_mfma_f32_16x16x32_bf16 v[8:11], v[170:173], v[210:213], v[8:11]
	v_mfma_f32_16x16x32_bf16 v[0:3], v[178:181], v[210:213], v[0:3]
	v_mfma_f32_16x16x32_bf16 v[56:59], v[174:177], v[190:193], v[56:59]
	v_mfma_f32_16x16x32_bf16 v[48:51], v[182:185], v[190:193], v[48:51]
	v_mfma_f32_16x16x32_bf16 v[40:43], v[174:177], v[198:201], v[40:43]
	v_mfma_f32_16x16x32_bf16 v[32:35], v[182:185], v[198:201], v[32:35]
	v_mfma_f32_16x16x32_bf16 v[24:27], v[174:177], v[206:209], v[24:27]
	v_mfma_f32_16x16x32_bf16 v[16:19], v[182:185], v[206:209], v[16:19]
	v_mfma_f32_16x16x32_bf16 v[8:11], v[174:177], v[214:217], v[8:11]
	v_mfma_f32_16x16x32_bf16 v[0:3], v[182:185], v[214:217], v[0:3]
	s_setprio 0
	s_barrier
	s_add_i32 s62, s62, 2
	s_add_u32 s36, s36, 0x100
	s_addc_u32 s37, s37, 0
	s_add_u32 s60, s60, 0x100
	s_addc_u32 s61, s61, 0
	s_cmp_gt_u32 s62, 13
	s_cbranch_scc0 .LBB0_1342
	s_and_b64 vcc, exec, s[12:13]
	s_cbranch_vccz .LBB0_1345
	s_barrier
